# store-issue-bound tails: GDN prep 5b products 0/2 store four dwordx4 (halves exchanged by v_permlane16_swap) instead of eight dwordx2
# speedup vs baseline: 1.0056x; 1.0056x over previous
;     ...
;             for (int k8 = 0; k8 < 8; ++k8) { const int tt = (w & 1) * 8 + k8, mt = tt >> 2, nt = tt & 3;
;                 if (prod == 0 || prod == 2) { const int off = ((nt * 2 + (mt >> 1)) * 64 + ((mt & 1) * 2 + (lq >> 1)) * 16 + lr) * 8 + 4 * (lq & 1); __builtin_nontemporal_store(res[k8], (v2u*)(gout + off)); }
;                 else if ((k8 & 1) == 0) { v4u pr2; pr2.x = res[k8].x; pr2.y = res[k8].y; pr2.z = res[k8 + 1].x; pr2.w = res[k8 + 1].y;
;                     __builtin_nontemporal_store(pr2, (v4u*)(gout + ((mt * 2 + (nt >> 1)) * 64 + lane) * 8)); } }
.Lst5b_m:
	v_mbcnt_lo_u32_b32 v28, -1, 0
	v_mbcnt_hi_u32_b32 v28, -1, v28
	v_and_b32_e32 v28, 16, v28
	v_lshlrev_b32_e32 v29, 7, v28
	v_lshrrev_b32_e32 v28, 1, v28
	v_sub_u32_e32 v29, v29, v28
	v_add_u32_e32 v28, v124, v29
	v_add_u32_e32 v29, 0x1000, v28
	v_permlane16_swap_b32_e32 v4, v6
	v_permlane16_swap_b32_e32 v5, v7
	v_permlane16_swap_b32_e32 v20, v22
	v_permlane16_swap_b32_e32 v21, v23
	v_permlane16_swap_b32_e32 v16, v18
	v_permlane16_swap_b32_e32 v17, v19
	v_permlane16_swap_b32_e32 v10, v12
	v_permlane16_swap_b32_e32 v11, v13
	global_store_dwordx4 v28, v[4:7], s[48:49] nt
	global_store_dwordx4 v29, v[20:23], s[48:49] nt
	global_store_dwordx4 v28, v[16:19], s[48:49] offset:512 nt
	global_store_dwordx4 v29, v[10:13], s[48:49] offset:512 nt
	s_and_saveexec_b64 s[12:13], s[42:43]
	s_cbranch_execz .LBB0_645
	s_branch .LBB0_685
